# SSD prompt loop: S1/S2/S3 LDS operand reads batched with counted waits; DPP cumsum
# speedup vs baseline: 1.0718x; 1.0153x over previous
.LBB0_188:
	s_or_b64 exec, exec, s[14:15]
	ds_read_b64_tr_b16 v[148:149], v136
	ds_read_b64_tr_b16 v[150:151], v136 offset:320
	ds_read_b64_tr_b16 v[152:153], v136 offset:32
	ds_read_b64_tr_b16 v[154:155], v136 offset:352
	ds_read_b64_tr_b16 v[156:157], v136 offset:2560
	ds_read_b64_tr_b16 v[158:159], v136 offset:2880
	ds_read_b64_tr_b16 v[160:161], v136 offset:2592
	ds_read_b64_tr_b16 v[162:163], v136 offset:2912
	ds_read_b64_tr_b16 v[164:165], v136 offset:5120
	ds_read_b64_tr_b16 v[166:167], v136 offset:5440
	v_mul_f32_e32 v27, 0x3fb8aa3b, v97
	v_exp_f32_e32 v28, v27
	s_waitcnt lgkmcnt(8)
	v_mfma_f32_16x16x32_bf16 v[66:69], v[148:151], v[62:65], 0
	ds_read_b64_tr_b16 v[168:169], v136 offset:5152
	ds_read_b64_tr_b16 v[170:171], v136 offset:5472
	s_waitcnt lgkmcnt(8)
	v_mfma_f32_16x16x32_bf16 v[62:65], v[152:155], v[62:65], 0
	ds_read_b64_tr_b16 v[220:221], v136 offset:7680
	ds_read_b64_tr_b16 v[222:223], v136 offset:8000
	ds_read_b64_tr_b16 v[224:225], v136 offset:7712
	ds_read_b64_tr_b16 v[226:227], v136 offset:8032
	ds_read_b32 v146, v122
	s_waitcnt lgkmcnt(11)
	v_mfma_f32_16x16x32_bf16 v[66:69], v[156:159], v[58:61], v[66:69]
	s_waitcnt lgkmcnt(9)
	v_mfma_f32_16x16x32_bf16 v[58:61], v[160:163], v[58:61], v[62:65]
	s_nop 2
	s_waitcnt lgkmcnt(7)
	v_mfma_f32_16x16x32_bf16 v[62:65], v[164:167], v[54:57], v[66:69]
	s_nop 2
	s_waitcnt lgkmcnt(5)
	v_mfma_f32_16x16x32_bf16 v[54:57], v[168:171], v[54:57], v[58:61]
	s_nop 2
	s_waitcnt lgkmcnt(3)
	v_mfma_f32_16x16x32_bf16 v[58:61], v[220:223], v[50:53], v[62:65]
	s_nop 2
	s_waitcnt lgkmcnt(0)
	v_div_scale_f32 v29, s[14:15], v146, v146, v99
	v_mfma_f32_16x16x32_bf16 v[50:53], v[224:227], v[50:53], v[54:57]
	v_readlane_b32 s14, v254, 15
	s_nop 1
	v_rcp_f32_e32 v54, v29
	s_nop 0
	v_fma_f32 v55, -v29, v54, 1.0
	v_fmac_f32_e32 v54, v55, v54
	v_div_scale_f32 v55, vcc, v99, v146, v99
	v_mul_f32_e32 v56, v55, v54
	v_fma_f32 v57, -v29, v56, v55
	v_fmac_f32_e32 v56, v57, v54
	v_fma_f32 v29, -v29, v56, v55
	v_div_fmas_f32 v29, v29, v54, v56
	v_add_u32_e32 v54, s33, v105
	v_ashrrev_i32_e32 v55, 31, v54
	v_lshlrev_b64 v[54:55], 11, v[54:55]
	v_lshl_add_u64 v[64:65], v[110:111], 0, v[54:55]
	ds_read2_b64 v[54:57], v123 offset1:4
	v_div_fixup_f32 v62, v29, v146, v99
	v_pk_fma_f32 v[60:61], v[28:29], v[60:61], v[88:89] op_sel_hi:[0,1,1]
	v_pk_fma_f32 v[58:59], v[28:29], v[58:59], v[86:87] op_sel_hi:[0,1,1]
	v_pk_fma_f32 v[52:53], v[28:29], v[52:53], v[84:85] op_sel_hi:[0,1,1]
	s_waitcnt lgkmcnt(0)
	v_lshlrev_b32_e32 v66, 16, v54
	v_and_b32_e32 v67, 0xffff0000, v54
	v_lshlrev_b32_e32 v54, 16, v55
	v_and_b32_e32 v55, 0xffff0000, v55
	v_pk_fma_f32 v[54:55], v[62:63], v[54:55], v[60:61] op_sel_hi:[0,1,1]
	v_pk_fma_f32 v[58:59], v[62:63], v[66:67], v[58:59] op_sel_hi:[0,1,1]
	v_pk_fma_f32 v[28:29], v[28:29], v[50:51], v[82:83] op_sel_hi:[0,1,1]
	v_lshlrev_b32_e32 v50, 16, v56
	v_and_b32_e32 v51, 0xffff0000, v56
	v_mov_b32_e32 v27, s14
	v_cvt_pk_bf16_f32 v58, v58, v59
	v_cvt_pk_bf16_f32 v59, v54, v55
	v_lshlrev_b32_e32 v54, 16, v57
	v_and_b32_e32 v55, 0xffff0000, v57
	v_pk_fma_f32 v[28:29], v[62:63], v[50:51], v[28:29] op_sel_hi:[0,1,1]
	ds_read_b32 v27, v27
	global_store_dwordx2 v[64:65], v[58:59], off
	v_pk_fma_f32 v[52:53], v[62:63], v[54:55], v[52:53] op_sel_hi:[0,1,1]
	v_cvt_pk_bf16_f32 v28, v28, v29
	v_cvt_pk_bf16_f32 v29, v52, v53
	global_store_dwordx2 v[64:65], v[28:29], off offset:32
	ds_read_b64_tr_b16 v[148:149], v137 offset:34816
	ds_read_b64_tr_b16 v[150:151], v137 offset:35904
	ds_read_b64_tr_b16 v[152:153], v138
	ds_read_b64_tr_b16 v[154:155], v138 offset:320
	ds_read_b64_tr_b16 v[156:157], v138 offset:32
	ds_read_b64_tr_b16 v[158:159], v138 offset:352
	ds_read_b64_tr_b16 v[160:161], v137 offset:43520
	ds_read_b64_tr_b16 v[162:163], v137 offset:44608
	ds_read_b64_tr_b16 v[164:165], v138 offset:2560
	ds_read_b64_tr_b16 v[166:167], v138 offset:2880
	ds_read_b64_tr_b16 v[168:169], v138 offset:2592
	ds_read_b64_tr_b16 v[170:171], v138 offset:2912
	s_waitcnt lgkmcnt(12)
	v_mul_f32_e32 v27, 0x3fb8aa3b, v27
	v_exp_f32_e32 v28, v27
	s_addk_i32 s33, 0x80
	s_cmpk_lg_i32 s33, 0x800
	v_pk_mul_f32 v[44:45], v[44:45], v[28:29] op_sel_hi:[1,0]
	v_pk_mul_f32 v[42:43], v[42:43], v[28:29] op_sel_hi:[1,0]
	v_pk_mul_f32 v[48:49], v[48:49], v[28:29] op_sel_hi:[1,0]
	v_pk_mul_f32 v[46:47], v[46:47], v[28:29] op_sel_hi:[1,0]
	s_waitcnt lgkmcnt(8)
	v_mfma_f32_16x16x32_bf16 v[42:45], v[152:155], v[148:151], v[42:45]
	s_waitcnt lgkmcnt(6)
	v_mfma_f32_16x16x32_bf16 v[46:49], v[156:159], v[148:151], v[46:49]
	ds_read_b64_tr_b16 v[220:221], v137 offset:52224
	ds_read_b64_tr_b16 v[222:223], v137 offset:53312
	ds_read_b64_tr_b16 v[224:225], v138 offset:5120
	ds_read_b64_tr_b16 v[226:227], v138 offset:5440
	ds_read_b64_tr_b16 v[232:233], v138 offset:5152
	ds_read_b64_tr_b16 v[234:235], v138 offset:5472
	s_waitcnt lgkmcnt(8)
	v_mfma_f32_16x16x32_bf16 v[42:45], v[164:167], v[160:163], v[42:45]
	s_waitcnt lgkmcnt(6)
	v_mfma_f32_16x16x32_bf16 v[46:49], v[168:171], v[160:163], v[46:49]
	ds_read_b64_tr_b16 v[236:237], v137 offset:60928
	ds_read_b64_tr_b16 v[238:239], v137 offset:62016
	ds_read_b64_tr_b16 v[240:241], v138 offset:7680
	ds_read_b64_tr_b16 v[242:243], v138 offset:8000
	ds_read_b64_tr_b16 v[244:245], v138 offset:7712
	ds_read_b64_tr_b16 v[246:247], v138 offset:8032
	s_waitcnt lgkmcnt(8)
	v_mfma_f32_16x16x32_bf16 v[42:45], v[224:227], v[220:223], v[42:45]
	s_waitcnt lgkmcnt(6)
	v_mfma_f32_16x16x32_bf16 v[46:49], v[232:235], v[220:223], v[46:49]
	s_waitcnt lgkmcnt(2)
	v_mfma_f32_16x16x32_bf16 v[42:45], v[240:243], v[236:239], v[42:45]
	s_waitcnt lgkmcnt(0)
	s_barrier
	s_nop 5
	v_mov_b32_e32 v27, v43
	v_mfma_f32_16x16x32_bf16 v[46:49], v[244:247], v[236:239], v[46:49]
	v_mov_b32_e32 v28, v44
	v_mov_b32_e32 v50, v45
	s_nop 5
	v_mov_b32_e32 v29, v46
	v_mov_b32_e32 v51, v47
	v_mov_b32_e32 v52, v48
	v_mov_b32_e32 v53, v49
	s_cbranch_scc0 .LBB0_186
.LBB0_189:
	s_and_saveexec_b64 s[14:15], s[4:5]
	s_cbranch_execz .LBB0_191
	s_waitcnt vmcnt(0)
	v_add_f32_e32 v54, v106, v107
	v_mul_f32_e64 v55, v54, -v95
	s_nop 1
	v_add_f32_dpp v55, v55, v55 row_shr:1 row_mask:0xf bank_mask:0xf bound_ctrl:0
	s_nop 1
	v_add_f32_dpp v55, v55, v55 row_shr:2 row_mask:0xf bank_mask:0xf bound_ctrl:0
	s_nop 1
	v_add_f32_dpp v55, v55, v55 row_shr:4 row_mask:0xf bank_mask:0xf bound_ctrl:0
	s_nop 1
	v_add_f32_dpp v55, v55, v55 row_shr:8 row_mask:0xf bank_mask:0xf bound_ctrl:0
	s_nop 1
	v_add_f32_dpp v55, v55, v55 row_bcast:15 row_mask:0xa bank_mask:0xf
	s_nop 1
	v_add_f32_dpp v55, v55, v55 row_bcast:31 row_mask:0xc bank_mask:0xf
	s_nop 1
	v_fma_f32 v54, v54, v95, v55
	v_fma_f32 v54, -v95, v106, v54
	ds_write_b64 v115, v[54:55]
	ds_write_b64 v116, v[106:107]

.LBB0_193:
	ds_read_b128 v[58:61], v135 offset:64
	ds_read_b128 v[54:57], v135 offset:128
	ds_read_b128 v[50:53], v135 offset:192
	ds_read_b128 v[62:65], v135
	ds_read_b32 v97, v121
	v_mov_b32_e32 v27, v26
	v_mov_b64_e32 v[72:73], v[28:29]
	v_mov_b64_e32 v[70:71], v[26:27]
	ds_read_b128 v[180:183], v139 offset:34816
	ds_read_b128 v[184:187], v139 offset:34880
	ds_read_b128 v[188:191], v139 offset:34944
	ds_read_b128 v[192:195], v139 offset:35008
	ds_read_b128 v[196:199], v125
	s_and_saveexec_b64 vcc, s[18:19]
	s_cbranch_execz .LBB0_195
	ds_read_b128 v[200:203], v139 offset:39168
	ds_read_b128 v[204:207], v139 offset:39232
	ds_read_b128 v[208:211], v139 offset:39296
	ds_read_b128 v[212:215], v139 offset:39360
	ds_read_b128 v[216:219], v126
	s_waitcnt lgkmcnt(9)
	v_mfma_f32_16x16x32_bf16 v[66:69], v[180:183], v[62:65], 0
	s_waitcnt lgkmcnt(8)
	v_mfma_f32_16x16x32_bf16 v[66:69], v[184:187], v[58:61], v[66:69]
	s_waitcnt lgkmcnt(7)
	v_mfma_f32_16x16x32_bf16 v[66:69], v[188:191], v[54:57], v[66:69]
	s_waitcnt lgkmcnt(6)
	v_mfma_f32_16x16x32_bf16 v[66:69], v[192:195], v[50:53], v[66:69]
	s_waitcnt lgkmcnt(5)
	s_nop 1
	v_sub_f32_e32 v27, v97, v196
	v_mul_f32_e32 v27, 0x3fb8aa3b, v27
	v_exp_f32_e32 v27, v27
	v_sub_f32_e32 v28, v97, v197
	v_sub_f32_e32 v29, v97, v198
	v_mul_f32_e32 v28, 0x3fb8aa3b, v28
	v_mul_f32_e32 v27, v66, v27
	v_sub_f32_e32 v66, v97, v199
	v_mul_f32_e32 v29, 0x3fb8aa3b, v29
	v_mul_f32_e32 v66, 0x3fb8aa3b, v66
	v_exp_f32_e32 v28, v28
	v_exp_f32_e32 v29, v29
	v_exp_f32_e32 v66, v66
	v_cndmask_b32_e64 v27, v27, 0, s[42:43]
	v_mul_f32_e32 v28, v67, v28
	v_mul_f32_e32 v29, v68, v29
	v_mul_f32_e32 v66, v69, v66
	v_cndmask_b32_e64 v28, 0, v28, s[44:45]
	v_cndmask_b32_e64 v29, v29, 0, s[46:47]
	v_cndmask_b32_e64 v66, v66, 0, s[48:49]
	v_cvt_pk_bf16_f32 v70, v27, v28
	v_cvt_pk_bf16_f32 v71, v29, v66
.LBB0_195:
	s_or_b64 exec, exec, vcc
	v_mov_b32_e32 v68, 0
	v_mov_b32_e32 v72, 0
	v_mov_b32_e32 v73, 0
	s_and_saveexec_b64 vcc, s[28:29]
	s_cbranch_execz .LBB0_197
	ds_read_b128 v[180:183], v139 offset:43520
	ds_read_b128 v[184:187], v139 offset:43584
	ds_read_b128 v[188:191], v139 offset:43648
	ds_read_b128 v[192:195], v139 offset:43712
	ds_read_b128 v[196:199], v127
	s_waitcnt lgkmcnt(9)
	v_mfma_f32_16x16x32_bf16 v[72:75], v[200:203], v[62:65], 0
	s_waitcnt lgkmcnt(8)
	v_mfma_f32_16x16x32_bf16 v[72:75], v[204:207], v[58:61], v[72:75]
	s_waitcnt lgkmcnt(7)
	v_mfma_f32_16x16x32_bf16 v[72:75], v[208:211], v[54:57], v[72:75]
	s_waitcnt lgkmcnt(6)
	v_mfma_f32_16x16x32_bf16 v[72:75], v[212:215], v[50:53], v[72:75]
	s_waitcnt lgkmcnt(5)
	s_nop 1
	v_sub_f32_e32 v27, v97, v216
	v_sub_f32_e32 v28, v97, v217
	v_sub_f32_e32 v29, v97, v218
	v_sub_f32_e32 v66, v97, v219
	v_mul_f32_e32 v27, 0x3fb8aa3b, v27
	v_mul_f32_e32 v28, 0x3fb8aa3b, v28
	v_mul_f32_e32 v29, 0x3fb8aa3b, v29
	v_mul_f32_e32 v66, 0x3fb8aa3b, v66
	v_exp_f32_e32 v27, v27
	v_exp_f32_e32 v28, v28
	v_exp_f32_e32 v29, v29
	v_exp_f32_e32 v66, v66
	v_mul_f32_e32 v27, v72, v27
	v_mul_f32_e32 v28, v73, v28
	v_mul_f32_e32 v29, v74, v29
	v_mul_f32_e32 v66, v75, v66
	v_cndmask_b32_e64 v27, v27, 0, s[52:53]
	v_cndmask_b32_e64 v28, v28, 0, s[54:55]
	v_cndmask_b32_e64 v29, v29, 0, s[56:57]
	v_cndmask_b32_e64 v66, v66, 0, s[58:59]
	v_cvt_pk_bf16_f32 v72, v27, v28
	v_cvt_pk_bf16_f32 v73, v29, v66
.LBB0_197:
	s_or_b64 exec, exec, vcc
	v_mov_b32_e32 v66, 0
	v_mov_b32_e32 v67, 0
	s_and_saveexec_b64 vcc, s[40:41]
	s_cbranch_execz .LBB0_199
	ds_read_b128 v[200:203], v139 offset:47872
	ds_read_b128 v[204:207], v139 offset:47936
	ds_read_b128 v[208:211], v139 offset:48000
	ds_read_b128 v[212:215], v139 offset:48064
	ds_read_b128 v[216:219], v128
	s_waitcnt lgkmcnt(9)
	v_mfma_f32_16x16x32_bf16 v[74:77], v[180:183], v[62:65], 0
	s_waitcnt lgkmcnt(8)
	v_mfma_f32_16x16x32_bf16 v[74:77], v[184:187], v[58:61], v[74:77]
	s_waitcnt lgkmcnt(7)
	v_mfma_f32_16x16x32_bf16 v[74:77], v[188:191], v[54:57], v[74:77]
	s_waitcnt lgkmcnt(6)
	v_mfma_f32_16x16x32_bf16 v[74:77], v[192:195], v[50:53], v[74:77]
	s_waitcnt lgkmcnt(5)
	s_nop 1
	v_sub_f32_e32 v66, v97, v199
	v_sub_f32_e32 v27, v97, v196
	v_sub_f32_e32 v28, v97, v197
	v_sub_f32_e32 v29, v97, v198
	v_mul_f32_e32 v66, 0x3fb8aa3b, v66
	v_mul_f32_e32 v27, 0x3fb8aa3b, v27
	v_mul_f32_e32 v28, 0x3fb8aa3b, v28
	v_mul_f32_e32 v29, 0x3fb8aa3b, v29
	v_exp_f32_e32 v66, v66
	v_exp_f32_e32 v27, v27
	v_exp_f32_e32 v28, v28
	v_exp_f32_e32 v29, v29
	v_mul_f32_e32 v66, v77, v66
	v_mul_f32_e32 v27, v74, v27
	v_mul_f32_e32 v28, v75, v28
	v_mul_f32_e32 v29, v76, v29
	v_cndmask_b32_e64 v67, v66, 0, s[68:69]
	v_cndmask_b32_e64 v27, v27, 0, s[62:63]
	v_cndmask_b32_e64 v28, v28, 0, s[64:65]
	v_cndmask_b32_e64 v29, v29, 0, s[66:67]
	v_cvt_pk_bf16_f32 v66, v27, v28
	v_cvt_pk_bf16_f32 v67, v29, v67
.LBB0_199:
	s_or_b64 exec, exec, vcc
	v_mov_b32_e32 v69, 0
	s_and_saveexec_b64 vcc, s[50:51]
	s_cbranch_execz .LBB0_201
	ds_read_b128 v[180:183], v139 offset:52224
	ds_read_b128 v[184:187], v139 offset:52288
	ds_read_b128 v[188:191], v139 offset:52352
	ds_read_b128 v[192:195], v139 offset:52416
	ds_read_b128 v[196:199], v129
	s_waitcnt lgkmcnt(9)
	v_mfma_f32_16x16x32_bf16 v[74:77], v[200:203], v[62:65], 0
	s_waitcnt lgkmcnt(8)
	v_mfma_f32_16x16x32_bf16 v[74:77], v[204:207], v[58:61], v[74:77]
	s_waitcnt lgkmcnt(7)
	v_mfma_f32_16x16x32_bf16 v[74:77], v[208:211], v[54:57], v[74:77]
	s_waitcnt lgkmcnt(6)
	v_mfma_f32_16x16x32_bf16 v[74:77], v[212:215], v[50:53], v[74:77]
	s_waitcnt lgkmcnt(5)
	s_nop 1
	v_sub_f32_e32 v68, v97, v219
	v_sub_f32_e32 v27, v97, v216
	v_sub_f32_e32 v28, v97, v217
	v_sub_f32_e32 v29, v97, v218
	v_mul_f32_e32 v68, 0x3fb8aa3b, v68
	v_mul_f32_e32 v27, 0x3fb8aa3b, v27
	v_mul_f32_e32 v28, 0x3fb8aa3b, v28
	v_mul_f32_e32 v29, 0x3fb8aa3b, v29
	v_exp_f32_e32 v68, v68
	v_exp_f32_e32 v27, v27
	v_exp_f32_e32 v28, v28
	v_exp_f32_e32 v29, v29
	v_mul_f32_e32 v68, v77, v68
	v_mul_f32_e32 v27, v74, v27
	v_mul_f32_e32 v28, v75, v28
	v_mul_f32_e32 v29, v76, v29
	v_cndmask_b32_e64 v69, v68, 0, s[78:79]
	v_cndmask_b32_e64 v27, v27, 0, s[72:73]
	v_cndmask_b32_e64 v28, v28, 0, s[74:75]
	v_cndmask_b32_e64 v29, v29, 0, s[76:77]
	v_cvt_pk_bf16_f32 v68, v27, v28
	v_cvt_pk_bf16_f32 v69, v29, v69
.LBB0_201:
	s_or_b64 exec, exec, vcc
	v_mov_b32_e32 v76, 0
	v_mov_b32_e32 v74, 0
	v_mov_b32_e32 v75, 0
	s_and_saveexec_b64 vcc, s[60:61]
	s_cbranch_execz .LBB0_203
	ds_read_b128 v[200:203], v139 offset:56576
	ds_read_b128 v[204:207], v139 offset:56640
	ds_read_b128 v[208:211], v139 offset:56704
	ds_read_b128 v[212:215], v139 offset:56768
	ds_read_b128 v[216:219], v130
	s_waitcnt lgkmcnt(9)
	v_mfma_f32_16x16x32_bf16 v[78:81], v[180:183], v[62:65], 0
	s_waitcnt lgkmcnt(8)
	v_mfma_f32_16x16x32_bf16 v[78:81], v[184:187], v[58:61], v[78:81]
	s_waitcnt lgkmcnt(7)
	v_mfma_f32_16x16x32_bf16 v[78:81], v[188:191], v[54:57], v[78:81]
	s_waitcnt lgkmcnt(6)
	v_mfma_f32_16x16x32_bf16 v[78:81], v[192:195], v[50:53], v[78:81]
	s_waitcnt lgkmcnt(5)
	s_nop 1
	v_sub_f32_e32 v74, v97, v199
	v_sub_f32_e32 v27, v97, v196
	v_sub_f32_e32 v28, v97, v197
	v_sub_f32_e32 v29, v97, v198
	v_mul_f32_e32 v74, 0x3fb8aa3b, v74
	v_mul_f32_e32 v27, 0x3fb8aa3b, v27
	v_mul_f32_e32 v28, 0x3fb8aa3b, v28
	v_mul_f32_e32 v29, 0x3fb8aa3b, v29
	v_exp_f32_e32 v74, v74
	v_exp_f32_e32 v27, v27
	v_exp_f32_e32 v28, v28
	v_exp_f32_e32 v29, v29
	v_mul_f32_e32 v74, v81, v74
	v_mul_f32_e32 v27, v78, v27
	v_mul_f32_e32 v28, v79, v28
	v_mul_f32_e32 v29, v80, v29
	v_cndmask_b32_e64 v75, v74, 0, s[88:89]
	v_cndmask_b32_e64 v27, v27, 0, s[82:83]
	v_cndmask_b32_e64 v28, v28, 0, s[84:85]
	v_cndmask_b32_e64 v29, v29, 0, s[86:87]
	v_cvt_pk_bf16_f32 v74, v27, v28
	v_cvt_pk_bf16_f32 v75, v29, v75
.LBB0_203:
	s_or_b64 exec, exec, vcc
	v_mov_b32_e32 v77, 0
	s_and_saveexec_b64 vcc, s[2:3]
	s_cbranch_execz .LBB0_205
	ds_read_b128 v[180:183], v139 offset:60928
	ds_read_b128 v[184:187], v139 offset:60992
	ds_read_b128 v[188:191], v139 offset:61056
	ds_read_b128 v[192:195], v139 offset:61120
	ds_read_b128 v[196:199], v131
	s_waitcnt lgkmcnt(9)
	v_mfma_f32_16x16x32_bf16 v[76:79], v[200:203], v[62:65], 0
	s_waitcnt lgkmcnt(8)
	v_mfma_f32_16x16x32_bf16 v[76:79], v[204:207], v[58:61], v[76:79]
	s_waitcnt lgkmcnt(7)
	v_mfma_f32_16x16x32_bf16 v[76:79], v[208:211], v[54:57], v[76:79]
	s_waitcnt lgkmcnt(6)
	v_mfma_f32_16x16x32_bf16 v[76:79], v[212:215], v[50:53], v[76:79]
	s_waitcnt lgkmcnt(5)
	s_nop 1
	v_sub_f32_e32 v27, v97, v216
	v_mul_f32_e32 v27, 0x3fb8aa3b, v27
	v_exp_f32_e32 v27, v27
	v_sub_f32_e32 v28, v97, v217
	v_sub_f32_e32 v29, v97, v218
	v_mul_f32_e32 v28, 0x3fb8aa3b, v28
	v_mul_f32_e32 v27, v76, v27
	v_sub_f32_e32 v76, v97, v219
	v_mul_f32_e32 v76, 0x3fb8aa3b, v76
	v_mul_f32_e32 v29, 0x3fb8aa3b, v29
	v_exp_f32_e32 v76, v76
	v_exp_f32_e32 v28, v28
	v_exp_f32_e32 v29, v29
	v_cndmask_b32_e64 v27, v27, 0, s[92:93]
	v_mul_f32_e32 v76, v79, v76
	v_mul_f32_e32 v28, v77, v28
	v_mul_f32_e32 v29, v78, v29
	v_cndmask_b32_e64 v77, v76, 0, s[80:81]
	v_cndmask_b32_e64 v28, v28, 0, s[94:95]
	v_cndmask_b32_e64 v29, v29, 0, s[70:71]
	v_cvt_pk_bf16_f32 v76, v27, v28
	v_cvt_pk_bf16_f32 v77, v29, v77
.LBB0_205:
	s_or_b64 exec, exec, vcc
	v_mov_b32_e32 v80, 0
	v_mov_b32_e32 v78, 0
	v_mov_b32_e32 v79, 0
	s_and_saveexec_b64 vcc, s[90:91]
	s_cbranch_execz .LBB0_207
	ds_read_b128 v[200:203], v139 offset:65280
	ds_read_b128 v[204:207], v139 offset:65344
	ds_read_b128 v[208:211], v139 offset:65408
	ds_read_b128 v[212:215], v139 offset:65472
	ds_read_b128 v[216:219], v132
	s_waitcnt lgkmcnt(9)
	v_mfma_f32_16x16x32_bf16 v[82:85], v[180:183], v[62:65], 0
	s_waitcnt lgkmcnt(8)
	v_mfma_f32_16x16x32_bf16 v[82:85], v[184:187], v[58:61], v[82:85]
	s_waitcnt lgkmcnt(7)
	v_mfma_f32_16x16x32_bf16 v[82:85], v[188:191], v[54:57], v[82:85]
	s_waitcnt lgkmcnt(6)
	v_mfma_f32_16x16x32_bf16 v[82:85], v[192:195], v[50:53], v[82:85]
	s_waitcnt lgkmcnt(5)
	s_nop 1
	v_sub_f32_e32 v78, v97, v199
	v_sub_f32_e32 v27, v97, v196
	v_sub_f32_e32 v28, v97, v197
	v_sub_f32_e32 v29, v97, v198
	v_mul_f32_e32 v78, 0x3fb8aa3b, v78
	v_mul_f32_e32 v27, 0x3fb8aa3b, v27
	v_mul_f32_e32 v28, 0x3fb8aa3b, v28
	v_mul_f32_e32 v29, 0x3fb8aa3b, v29
	v_exp_f32_e32 v78, v78
	v_exp_f32_e32 v27, v27
	v_exp_f32_e32 v28, v28
	v_exp_f32_e32 v29, v29
	v_mul_f32_e32 v78, v85, v78
	v_mul_f32_e32 v27, v82, v27
	v_mul_f32_e32 v28, v83, v28
	v_mul_f32_e32 v29, v84, v29
	v_cndmask_b32_e64 v79, v78, 0, s[10:11]
	v_cndmask_b32_e64 v27, v27, 0, s[6:7]
	v_cndmask_b32_e64 v28, v28, 0, s[0:1]
	v_cndmask_b32_e64 v29, v29, 0, s[8:9]
	v_cvt_pk_bf16_f32 v78, v27, v28
	v_cvt_pk_bf16_f32 v79, v29, v79
.LBB0_207:
	s_or_b64 exec, exec, vcc
	v_mov_b32_e32 v81, 0
	s_mov_b64 vcc, exec
	v_readlane_b32 s14, v255, 28
	v_readlane_b32 s15, v255, 29
	s_and_b64 s[14:15], vcc, s[14:15]
	s_mov_b64 exec, s[14:15]
	s_cbranch_execz .LBB0_209
	v_readlane_b32 s14, v255, 30
	v_readlane_b32 s15, v255, 31
	s_waitcnt lgkmcnt(4)
	v_mfma_f32_16x16x32_bf16 v[80:83], v[200:203], v[62:65], 0
	s_waitcnt lgkmcnt(3)
	v_mfma_f32_16x16x32_bf16 v[80:83], v[204:207], v[58:61], v[80:83]
	s_waitcnt lgkmcnt(2)
	v_mfma_f32_16x16x32_bf16 v[80:83], v[208:211], v[54:57], v[80:83]
	s_waitcnt lgkmcnt(1)
	v_mfma_f32_16x16x32_bf16 v[80:83], v[212:215], v[50:53], v[80:83]
	s_waitcnt lgkmcnt(0)
	s_nop 1
	v_sub_f32_e32 v27, v97, v216
	v_mul_f32_e32 v27, 0x3fb8aa3b, v27
	v_exp_f32_e32 v27, v27
	v_sub_f32_e32 v28, v97, v217
	v_mul_f32_e32 v28, 0x3fb8aa3b, v28
	v_exp_f32_e32 v28, v28
	v_sub_f32_e32 v29, v97, v218
	v_mul_f32_e32 v29, 0x3fb8aa3b, v29
	v_mul_f32_e32 v27, v80, v27
	v_exp_f32_e32 v29, v29
	v_sub_f32_e32 v80, v97, v219
	v_cndmask_b32_e64 v27, v27, 0, s[14:15]
	v_readlane_b32 s14, v255, 32
	v_mul_f32_e32 v80, 0x3fb8aa3b, v80
	v_mul_f32_e32 v28, v81, v28
	v_readlane_b32 s15, v255, 33
	v_exp_f32_e32 v80, v80
	v_mul_f32_e32 v29, v82, v29
	v_cndmask_b32_e64 v28, v28, 0, s[14:15]
	v_readlane_b32 s14, v255, 34
	v_readlane_b32 s15, v255, 35
	v_mul_f32_e32 v80, v83, v80
	s_nop 0
	v_cndmask_b32_e64 v29, v29, 0, s[14:15]
	v_readlane_b32 s14, v255, 36
	v_readlane_b32 s15, v255, 37
	s_nop 1
	v_cndmask_b32_e64 v81, v80, 0, s[14:15]
	v_cvt_pk_bf16_f32 v80, v27, v28
	v_cvt_pk_bf16_f32 v81, v29, v81
.LBB0_209:
	s_or_b64 exec, exec, vcc
	s_waitcnt lgkmcnt(0)
	s_barrier
	ds_read_b64_tr_b16 v[180:181], v140
	ds_read_b64_tr_b16 v[182:183], v140 offset:1280
	ds_read_b64_tr_b16 v[184:185], v140 offset:32
	ds_read_b64_tr_b16 v[186:187], v140 offset:1312
	v_mov_b32_e32 v28, v26
	v_mov_b32_e32 v29, v26
	v_mov_b32_e32 v27, v26
	v_mov_b64_e32 v[84:85], v[28:29]
	v_mov_b64_e32 v[88:89], v[28:29]
	v_readlane_b32 s22, v255, 38
	v_mov_b64_e32 v[82:83], v[26:27]
	v_mov_b64_e32 v[86:87], v[26:27]
	v_readlane_b32 s23, v255, 39
	s_and_saveexec_b64 s[14:15], s[22:23]
	s_cbranch_execz .LBB0_211
	ds_read_b64_tr_b16 v[200:201], v140 offset:2560
	ds_read_b64_tr_b16 v[202:203], v140 offset:3840
	ds_read_b64_tr_b16 v[204:205], v140 offset:2592
	ds_read_b64_tr_b16 v[206:207], v140 offset:3872
	s_waitcnt lgkmcnt(6)
	v_mfma_f32_16x16x32_bf16 v[86:89], v[180:183], v[70:73], 0
	s_waitcnt lgkmcnt(4)
	v_mfma_f32_16x16x32_bf16 v[82:85], v[184:187], v[70:73], 0
.LBB0_211:
	s_or_b64 exec, exec, s[14:15]
	v_readlane_b32 s22, v255, 40
	v_readlane_b32 s23, v255, 41
	s_and_saveexec_b64 s[14:15], s[22:23]
	s_cbranch_execz .LBB0_213
	ds_read_b64_tr_b16 v[180:181], v140 offset:5120
	ds_read_b64_tr_b16 v[182:183], v140 offset:6400
	ds_read_b64_tr_b16 v[184:185], v140 offset:5152
	ds_read_b64_tr_b16 v[186:187], v140 offset:6432
	s_waitcnt lgkmcnt(6)
	v_mfma_f32_16x16x32_bf16 v[86:89], v[200:203], v[66:69], v[86:89]
	s_waitcnt lgkmcnt(4)
	v_mfma_f32_16x16x32_bf16 v[82:85], v[204:207], v[66:69], v[82:85]
.LBB0_213:
	s_or_b64 exec, exec, s[14:15]
	v_readlane_b32 s22, v255, 42
	v_readlane_b32 s23, v255, 43
	s_and_saveexec_b64 s[14:15], s[22:23]
	s_cbranch_execz .LBB0_215
	ds_read_b64_tr_b16 v[200:201], v140 offset:7680
	ds_read_b64_tr_b16 v[202:203], v140 offset:8960
	ds_read_b64_tr_b16 v[204:205], v140 offset:7712
	ds_read_b64_tr_b16 v[206:207], v140 offset:8992
	s_waitcnt lgkmcnt(6)
	v_mfma_f32_16x16x32_bf16 v[86:89], v[180:183], v[74:77], v[86:89]
	s_waitcnt lgkmcnt(4)
	v_mfma_f32_16x16x32_bf16 v[82:85], v[184:187], v[74:77], v[82:85]
.LBB0_215:
	s_or_b64 exec, exec, s[14:15]
	v_readlane_b32 s22, v255, 44
	v_readlane_b32 s23, v255, 45
	s_and_saveexec_b64 s[14:15], s[22:23]
	s_cbranch_execz .LBB0_188
	s_waitcnt lgkmcnt(2)
	v_mfma_f32_16x16x32_bf16 v[86:89], v[200:203], v[78:81], v[86:89]
	s_waitcnt lgkmcnt(0)
	v_mfma_f32_16x16x32_bf16 v[82:85], v[204:207], v[78:81], v[82:85]
	s_branch .LBB0_188
